# comb11y with the in-proj GEMM loop head back at byte phase 60 (unreachable padding after the phase 0 tile loop)
# speedup vs baseline: 1.0033x; 1.0033x over previous
.Lt0_w4_2:
	s_waitcnt vmcnt(4)
	s_branch .Lt0_st0
	s_nop 0
	s_nop 0
	s_nop 0
	s_nop 0
	s_nop 0
	s_nop 0
	s_nop 0
	s_nop 0
	s_nop 0
	s_nop 0
	s_nop 0
	s_nop 0
	s_nop 0
	s_nop 0
	s_nop 0
